# hg_post 16-lane sums and the final LayerNorm variance sum also moved from ds_bpermute to DPP row adds / permlane swaps
# baseline (speedup 1.0000x reference)
; DI unsigned pack2(float a, float b) { f32x2_t v = {a, b}; return __builtin_bit_cast(unsigned, __builtin_convertvector(v, bf16x2_t)); }
; DI float lo2f(unsigned v) { return __uint_as_float(v << 16); }
; DI float hi2f(unsigned v) { return __uint_as_float(v & 0xffff0000u); }
; DI float silu(float x) { return x * __builtin_amdgcn_rcpf(1.f + __expf(-x)); }
; DI void hg_post_phase(int wvs, const bf16_t* __restrict__ ZB, bf16_t* OF, const bf16_t* __restrict__ OB, const float* __restrict__ norm_g, bool dostore = true) {
;     ...
;   for (int itw = blockIdx.x * 8 + w; itw < MH * 4; itw += gridDim.x * 8) {
;     const int m = itw >> 2, grp = itw & 3, col = grp * 512 + lane * 8;
;     const u32x4 yf = *(const u32x4*)(OF + (size_t)m * 2048 + col);
;     const u32x4 yb = *(const u32x4*)(OB + (size_t)m * 2048 + col);
;     const u32x4 zz = *(const u32x4*)(ZB + (size_t)m * 2048 + col);
;     float v[8];
;     float ss = 0.f;
; #pragma unroll
;     for (int j = 0; j < 4; ++j) {
;       v[2 * j] = lo2f(yf[j]) + lo2f(yb[j]);
;       v[2 * j + 1] = hi2f(yf[j]) + hi2f(yb[j]);
;       ss += v[2 * j] * v[2 * j] + v[2 * j + 1] * v[2 * j + 1];
;     }
;     ss += __shfl_xor(ss, 1); ss += __shfl_xor(ss, 2); ss += __shfl_xor(ss, 4); ss += __shfl_xor(ss, 8);
;     const float sc = rsqrtf(ss * (1.f / 128.f) + 1e-5f);
;     const float4 g0 = *(const float4*)(norm_g + col), g1 = *(const float4*)(norm_g + col + 4);
;     u32x4 o;
;     o[0] = pack2(v[0] * sc * g0.x * silu(lo2f(zz[0])), v[1] * sc * g0.y * silu(hi2f(zz[0])));
;     o[1] = pack2(v[2] * sc * g0.z * silu(lo2f(zz[1])), v[3] * sc * g0.w * silu(hi2f(zz[1])));
;     o[2] = pack2(v[4] * sc * g1.x * silu(lo2f(zz[2])), v[5] * sc * g1.y * silu(hi2f(zz[2])));
;     o[3] = pack2(v[6] * sc * g1.z * silu(lo2f(zz[3])), v[7] * sc * g1.w * silu(hi2f(zz[3])));
;     if (dostore) *(u32x4*)(OF + (size_t)m * 2048 + col) = o;
.LBB0_445:
	v_ashrrev_i32_e32 v8, 2, v0
	v_ashrrev_i32_e32 v9, 31, v8
	v_and_or_b32 v7, v6, s25, v1
	v_lshlrev_b64 v[16:17], 12, v[8:9]
	v_lshl_add_u64 v[8:9], s[94:95], 0, v[16:17]
	v_lshlrev_b32_e32 v128, 1, v7
	v_lshl_add_u64 v[12:13], s[22:23], 0, v[16:17]
	v_lshl_add_u64 v[28:29], v[8:9], 0, v[128:129]
	v_lshl_add_u64 v[12:13], v[12:13], 0, v[128:129]
	global_load_dwordx4 v[8:11], v[28:29], off
	v_lshl_add_u64 v[16:17], s[10:11], 0, v[16:17]
	global_load_dwordx4 v[12:15], v[12:13], off
	v_lshl_add_u64 v[16:17], v[16:17], 0, v[128:129]
	global_load_dwordx4 v[16:19], v[16:17], off
	v_lshlrev_b32_e32 v7, 2, v7
	v_add_u32_e32 v0, s13, v0
	v_add_u32_e32 v6, s24, v6
	s_waitcnt vmcnt(2)
	v_lshlrev_b32_e32 v20, 16, v11
	v_and_b32_e32 v21, 0xffff0000, v11
	s_waitcnt vmcnt(1)
	v_lshlrev_b32_e32 v22, 16, v15
	v_and_b32_e32 v23, 0xffff0000, v15
	v_lshlrev_b32_e32 v32, 16, v10
	v_and_b32_e32 v33, 0xffff0000, v10
	v_lshlrev_b32_e32 v10, 16, v14
	v_and_b32_e32 v11, 0xffff0000, v14
	v_pk_add_f32 v[30:31], v[20:21], v[22:23]
	v_pk_add_f32 v[10:11], v[32:33], v[10:11]
	v_mov_b32_e32 v14, v30
	v_mov_b32_e32 v15, v10
	v_pk_mul_f32 v[14:15], v[14:15], v[14:15]
	v_mov_b32_e32 v32, v31
	v_mov_b32_e32 v33, v11
	v_pk_fma_f32 v[14:15], v[32:33], v[32:33], v[14:15]
	s_waitcnt vmcnt(0)
	v_lshlrev_b32_e32 v32, 16, v18
	global_load_dwordx4 v[20:23], v7, s[54:55] offset:16
	global_load_dwordx4 v[24:27], v7, s[54:55]
	v_mul_f32_e32 v7, 0xbfb8aa3b, v32
	v_exp_f32_e32 v7, v7
	v_and_b32_e32 v33, 0xffff0000, v18
	v_lshlrev_b32_e32 v36, 16, v13
	v_and_b32_e32 v37, 0xffff0000, v13
	v_add_f32_e32 v7, 1.0, v7
	v_rcp_f32_e32 v34, v7
	v_mul_f32_e32 v7, 0xbfb8aa3b, v33
	v_exp_f32_e32 v7, v7
	s_nop 0
	v_add_f32_e32 v7, 1.0, v7
	v_rcp_f32_e32 v35, v7
	s_nop 0
	v_pk_mul_f32 v[32:33], v[34:35], v[32:33]
	v_lshlrev_b32_e32 v34, 16, v9
	v_and_b32_e32 v35, 0xffff0000, v9
	v_pk_add_f32 v[34:35], v[34:35], v[36:37]
	v_lshlrev_b32_e32 v36, 16, v17
	v_mul_f32_e32 v7, 0xbfb8aa3b, v36
	v_exp_f32_e32 v7, v7
	v_and_b32_e32 v37, 0xffff0000, v17
	v_and_b32_e32 v9, 0xffff0000, v12
	v_mov_b32_e32 v13, v34
	v_add_f32_e32 v7, 1.0, v7
	v_rcp_f32_e32 v38, v7
	v_mul_f32_e32 v7, 0xbfb8aa3b, v37
	v_exp_f32_e32 v7, v7
	s_nop 0
	v_add_f32_e32 v7, 1.0, v7
	v_rcp_f32_e32 v39, v7
	s_nop 0
	v_pk_mul_f32 v[36:37], v[38:39], v[36:37]
	v_lshlrev_b32_e32 v38, 16, v8
	v_and_b32_e32 v39, 0xffff0000, v8
	v_lshlrev_b32_e32 v8, 16, v12
	v_pk_add_f32 v[8:9], v[38:39], v[8:9]
	v_mov_b32_e32 v39, v35
	v_mov_b32_e32 v12, v8
	v_pk_mul_f32 v[12:13], v[12:13], v[12:13]
	v_mov_b32_e32 v38, v9
	v_pk_fma_f32 v[12:13], v[38:39], v[38:39], v[12:13]
	v_lshlrev_b32_e32 v38, 16, v16
	v_mul_f32_e32 v7, 0xbfb8aa3b, v38
	v_exp_f32_e32 v7, v7
	v_and_b32_e32 v39, 0xffff0000, v16
	v_add_f32_e32 v7, 1.0, v7
	v_rcp_f32_e32 v16, v7
	v_mul_f32_e32 v7, 0xbfb8aa3b, v39
	v_exp_f32_e32 v7, v7
	s_nop 0
	v_add_f32_e32 v7, 1.0, v7
	v_rcp_f32_e32 v17, v7
	v_add_f32_e32 v7, v12, v13
	v_add_f32_e32 v7, v15, v7
	v_add_f32_e32 v7, v14, v7
	v_pk_mul_f32 v[16:17], v[16:17], v[38:39]
	s_nop 1
	v_add_f32_dpp v7, v7, v7 quad_perm:[1,0,3,2] row_mask:0xf bank_mask:0xf
	s_nop 1
	v_add_f32_dpp v7, v7, v7 quad_perm:[2,3,0,1] row_mask:0xf bank_mask:0xf
	s_nop 1
	v_add_f32_dpp v7, v7, v7 row_half_mirror row_mask:0xf bank_mask:0xf
	s_nop 1
	v_add_f32_dpp v7, v7, v7 row_mirror row_mask:0xf bank_mask:0xf
	v_fmamk_f32 v7, v7, 0x3c000000, v177
	v_cmp_gt_f32_e32 vcc, s75, v7
	v_mul_f32_e32 v12, 0x4b800000, v7
	s_nop 0
	v_cndmask_b32_e32 v7, v7, v12, vcc
	v_rsq_f32_e32 v7, v7
	s_nop 0
	v_mul_f32_e32 v12, 0x45800000, v7
	v_cndmask_b32_e32 v12, v7, v12, vcc
	v_pk_mul_f32 v[8:9], v[8:9], v[12:13] op_sel_hi:[1,0]
	v_pk_mul_f32 v[14:15], v[34:35], v[12:13] op_sel_hi:[1,0]
	s_waitcnt vmcnt(0)
	v_pk_mul_f32 v[8:9], v[24:25], v[8:9]
	v_pk_mul_f32 v[14:15], v[26:27], v[14:15]
	v_pk_mul_f32 v[8:9], v[16:17], v[8:9]
	v_pk_mul_f32 v[14:15], v[36:37], v[14:15]
	v_cvt_pk_bf16_f32 v8, v8, v9
	v_cvt_pk_bf16_f32 v9, v14, v15
	v_lshlrev_b32_e32 v14, 16, v19
	v_mul_f32_e32 v7, 0xbfb8aa3b, v14
	v_exp_f32_e32 v7, v7
	v_and_b32_e32 v15, 0xffff0000, v19
	v_pk_mul_f32 v[10:11], v[10:11], v[12:13] op_sel_hi:[1,0]
	v_pk_mul_f32 v[12:13], v[30:31], v[12:13] op_sel_hi:[1,0]
	v_add_f32_e32 v7, 1.0, v7
	v_rcp_f32_e32 v16, v7
	v_mul_f32_e32 v7, 0xbfb8aa3b, v15
	v_exp_f32_e32 v7, v7
	v_pk_mul_f32 v[10:11], v[20:21], v[10:11]
	v_pk_mul_f32 v[12:13], v[22:23], v[12:13]
	v_pk_mul_f32 v[10:11], v[32:33], v[10:11]
	v_add_f32_e32 v7, 1.0, v7
	v_rcp_f32_e32 v17, v7
	v_cmp_lt_i32_e32 vcc, s28, v0
	v_cvt_pk_bf16_f32 v10, v10, v11
	s_or_b64 s[42:43], vcc, s[42:43]
	v_pk_mul_f32 v[14:15], v[16:17], v[14:15]
	s_nop 0
	v_pk_mul_f32 v[12:13], v[14:15], v[12:13]
	s_nop 0
	v_cvt_pk_bf16_f32 v11, v12, v13
	global_store_dwordx4 v[28:29], v[8:11], off
	s_andn2_b64 exec, exec, s[42:43]
	s_cbranch_execnz .LBB0_445

; DI unsigned pack2(float a, float b) { f32x2_t v = {a, b}; return __builtin_bit_cast(unsigned, __builtin_convertvector(v, bf16x2_t)); }
; DI float lo2f(unsigned v) { return __uint_as_float(v << 16); }
; DI float hi2f(unsigned v) { return __uint_as_float(v & 0xffff0000u); }
; DI float wave_sum(float v) { for (int o = 32; o >= 1; o >>= 1) v += __shfl_xor(v, o); return v; }
; DI void ln_phase(int wvs, bf16_t* HB, const float* __restrict__ g, const float* __restrict__ bta, float* fout, bool dostore = true) {
;     ...
;   for (int row = blockIdx.x * 8 + w; row < MTOT; row += gridDim.x * 8) {
;     bf16_t* p = HB + (size_t)row * 1024;
;     float v[16];
;     float s = 0.f;
; #pragma unroll
;     for (int i = 0; i < 2; ++i) {
;       const u32x4 raw = *(const u32x4*)(p + i * 512 + lane * 8);
; #pragma unroll
;       for (int j = 0; j < 4; ++j) { v[i * 8 + 2 * j] = lo2f(raw[j]); v[i * 8 + 2 * j + 1] = hi2f(raw[j]); }
;     }
; #pragma unroll
;     for (int i = 0; i < 16; ++i) s += v[i];
;     const float mean = wave_sum(s) * (1.f / 1024.f);
;     float q = 0.f;
; #pragma unroll
;     for (int i = 0; i < 16; ++i) { v[i] -= mean; q += v[i] * v[i]; }
;     const float rstd = rsqrtf(wave_sum(q) * (1.f / 1024.f) + 1e-5f);
; #pragma unroll
;     for (int i = 0; i < 2; ++i) {
;       const int c = i * 512 + lane * 8;
;       const float4 g0 = *(const float4*)(g + c), g1 = *(const float4*)(g + c + 4), b0 = *(const float4*)(bta + c), b1 = *(const float4*)(bta + c + 4);
;       float o[8];
;       o[0] = v[i * 8 + 0] * rstd * g0.x + b0.x; o[1] = v[i * 8 + 1] * rstd * g0.y + b0.y; o[2] = v[i * 8 + 2] * rstd * g0.z + b0.z; o[3] = v[i * 8 + 3] * rstd * g0.w + b0.w;
;       o[4] = v[i * 8 + 4] * rstd * g1.x + b1.x; o[5] = v[i * 8 + 5] * rstd * g1.y + b1.y; o[6] = v[i * 8 + 6] * rstd * g1.z + b1.z; o[7] = v[i * 8 + 7] * rstd * g1.w + b1.w;
;       if (dostore) {
;         u32x4 pk; pk[0] = pack2(o[0], o[1]); pk[1] = pack2(o[2], o[3]); pk[2] = pack2(o[4], o[5]); pk[3] = pack2(o[6], o[7]);
;         *(u32x4*)(p + c) = pk;
;         if (fout) {
;           *(float4*)(fout + (size_t)row * 1024 + c) = make_float4(o[0], o[1], o[2], o[3]);
;           *(float4*)(fout + (size_t)row * 1024 + c + 4) = make_float4(o[4], o[5], o[6], o[7]);
;         }
;       }
.LBB0_1445:
	v_ashrrev_i32_e32 v41, 31, v40
	v_lshlrev_b64 v[32:33], 11, v[40:41]
	v_lshl_add_u64 v[46:47], v[44:45], 0, v[32:33]
	global_load_dwordx4 v[32:35], v[46:47], off
	global_load_dwordx4 v[36:39], v[46:47], off offset:1024
	v_lshlrev_b64 v[48:49], 12, v[40:41]
	v_readlane_b32 s6, v253, 1
	v_readlane_b32 s7, v253, 2
	v_lshl_add_u64 v[48:49], s[10:11], 0, v[48:49]
	v_lshlrev_b32_e32 v128, 2, v42
	s_waitcnt vmcnt(1)
	v_lshlrev_b32_e32 v52, 16, v32
	v_and_b32_e32 v53, 0xffff0000, v32
	v_add_f32_e32 v32, 0, v52
	v_add_f32_e32 v41, v32, v53
	v_lshlrev_b32_e32 v32, 16, v33
	v_and_b32_e32 v33, 0xffff0000, v33
	v_add_f32_e32 v41, v41, v32
	v_add_f32_e32 v41, v41, v33
	v_lshlrev_b32_e32 v56, 16, v34
	v_and_b32_e32 v57, 0xffff0000, v34
	v_add_f32_e32 v34, v41, v56
	v_add_f32_e32 v41, v34, v57
	v_lshlrev_b32_e32 v34, 16, v35
	v_and_b32_e32 v35, 0xffff0000, v35
	v_add_f32_e32 v41, v41, v34
	s_waitcnt vmcnt(0)
	v_lshlrev_b32_e32 v50, 16, v36
	v_add_f32_e32 v41, v41, v35
	v_and_b32_e32 v51, 0xffff0000, v36
	v_add_f32_e32 v41, v41, v50
	v_lshlrev_b32_e32 v36, 16, v37
	v_add_f32_e32 v41, v41, v51
	v_and_b32_e32 v37, 0xffff0000, v37
	v_add_f32_e32 v41, v41, v36
	v_lshlrev_b32_e32 v54, 16, v38
	v_add_f32_e32 v41, v41, v37
	v_and_b32_e32 v55, 0xffff0000, v38
	v_add_f32_e32 v41, v41, v54
	v_lshlrev_b32_e32 v38, 16, v39
	v_add_f32_e32 v41, v41, v55
	v_and_b32_e32 v39, 0xffff0000, v39
	v_add_f32_e32 v41, v41, v38
	v_add_f32_e32 v41, v41, v39
	s_nop 1
	v_add_f32_dpp v41, v41, v41 quad_perm:[1,0,3,2] row_mask:0xf bank_mask:0xf
	s_nop 1
	v_add_f32_dpp v41, v41, v41 quad_perm:[2,3,0,1] row_mask:0xf bank_mask:0xf
	s_nop 1
	v_add_f32_dpp v41, v41, v41 row_half_mirror row_mask:0xf bank_mask:0xf
	s_nop 1
	v_add_f32_dpp v41, v41, v41 row_mirror row_mask:0xf bank_mask:0xf
	v_mov_b32_e32 v58, v41
	s_nop 1
	v_permlane16_swap_b32_e32 v58, v41
	v_add_f32_e32 v41, v41, v58
	v_mov_b32_e32 v58, v41
	s_nop 1
	v_permlane32_swap_b32_e32 v58, v41
	v_add_f32_e32 v41, v41, v58
	v_mul_f32_e32 v58, 0x3a800000, v41
	v_pk_add_f32 v[66:67], v[52:53], v[58:59] op_sel_hi:[1,0] neg_lo:[0,1] neg_hi:[0,1]
	v_pk_add_f32 v[32:33], v[32:33], v[58:59] op_sel_hi:[1,0] neg_lo:[0,1] neg_hi:[0,1]
	v_pk_mul_f32 v[68:69], v[66:67], v[66:67]
	v_pk_mul_f32 v[70:71], v[32:33], v[32:33]
	v_add_f32_e32 v41, v68, v69
	v_pk_add_f32 v[72:73], v[56:57], v[58:59] op_sel_hi:[1,0] neg_lo:[0,1] neg_hi:[0,1]
	v_add_f32_e32 v41, v70, v41
	v_pk_mul_f32 v[74:75], v[72:73], v[72:73]
	v_add_f32_e32 v41, v71, v41
	v_pk_add_f32 v[34:35], v[34:35], v[58:59] op_sel_hi:[1,0] neg_lo:[0,1] neg_hi:[0,1]
	v_add_f32_e32 v41, v74, v41
	v_pk_mul_f32 v[76:77], v[34:35], v[34:35]
	v_add_f32_e32 v41, v75, v41
	v_pk_add_f32 v[50:51], v[50:51], v[58:59] op_sel_hi:[1,0] neg_lo:[0,1] neg_hi:[0,1]
	v_add_f32_e32 v41, v76, v41
	v_pk_mul_f32 v[78:79], v[50:51], v[50:51]
	v_add_f32_e32 v41, v77, v41
	v_pk_add_f32 v[52:53], v[36:37], v[58:59] op_sel_hi:[1,0] neg_lo:[0,1] neg_hi:[0,1]
	v_add_f32_e32 v41, v78, v41
	v_pk_mul_f32 v[36:37], v[52:53], v[52:53]
	v_add_f32_e32 v41, v79, v41
	v_pk_add_f32 v[54:55], v[54:55], v[58:59] op_sel_hi:[1,0] neg_lo:[0,1] neg_hi:[0,1]
	v_add_f32_e32 v36, v36, v41
	v_pk_mul_f32 v[80:81], v[54:55], v[54:55]
	v_add_f32_e32 v36, v37, v36
	v_pk_add_f32 v[56:57], v[38:39], v[58:59] op_sel_hi:[1,0] neg_lo:[0,1] neg_hi:[0,1]
	v_add_f32_e32 v36, v80, v36
	v_pk_mul_f32 v[38:39], v[56:57], v[56:57]
	v_add_f32_e32 v36, v81, v36
	v_add_f32_e32 v36, v38, v36
	v_add_f32_e32 v36, v39, v36
	v_cndmask_b32_e64 v41, 0, 1, s[6:7]
	v_cmp_ne_u32_e64 s[40:41], 1, v41
	s_nop 1
	v_add_f32_dpp v36, v36, v36 quad_perm:[1,0,3,2] row_mask:0xf bank_mask:0xf
	s_nop 1
	v_add_f32_dpp v36, v36, v36 quad_perm:[2,3,0,1] row_mask:0xf bank_mask:0xf
	s_nop 1
	v_add_f32_dpp v36, v36, v36 row_half_mirror row_mask:0xf bank_mask:0xf
	s_nop 1
	v_add_f32_dpp v36, v36, v36 row_mirror row_mask:0xf bank_mask:0xf
	v_mov_b32_e32 v37, v36
	s_nop 1
	v_permlane16_swap_b32_e32 v37, v36
	v_add_f32_e32 v36, v36, v37
	v_mov_b32_e32 v37, v36
	s_nop 1
	v_permlane32_swap_b32_e32 v37, v36
	v_add_f32_e32 v36, v36, v37
	v_fmamk_f32 v36, v36, 0x3a800000, v177
	v_cmp_gt_f32_e32 vcc, s75, v36
	v_mul_f32_e32 v37, 0x4b800000, v36
	s_nop 0
	v_cndmask_b32_e32 v36, v36, v37, vcc
	v_rsq_f32_e32 v36, v36
	s_nop 0
	v_mul_f32_e32 v37, 0x45800000, v36
	v_cndmask_b32_e32 v58, v36, v37, vcc
	v_pk_mul_f32 v[32:33], v[32:33], v[58:59] op_sel_hi:[1,0]
	v_pk_mul_f32 v[36:37], v[66:67], v[58:59] op_sel_hi:[1,0]
	v_pk_fma_f32 v[38:39], v[10:11], v[32:33], v[14:15]
	v_pk_mul_f32 v[32:33], v[72:73], v[58:59] op_sel_hi:[1,0]
	v_pk_mul_f32 v[34:35], v[34:35], v[58:59] op_sel_hi:[1,0]
	v_pk_fma_f32 v[36:37], v[8:9], v[36:37], v[12:13]
	v_pk_fma_f32 v[32:33], v[0:1], v[32:33], v[4:5]
	v_pk_fma_f32 v[34:35], v[2:3], v[34:35], v[6:7]
	v_cvt_pk_bf16_f32 v66, v36, v37
	v_cvt_pk_bf16_f32 v67, v38, v39
	v_cvt_pk_bf16_f32 v68, v32, v33
	v_cvt_pk_bf16_f32 v69, v34, v35
	s_andn2_b64 vcc, exec, s[6:7]
	s_cbranch_vccnz .LBB0_1447
	s_nop 0
	v_lshl_add_u64 v[66:67], v[48:49], 0, v[128:129]
	global_store_dwordx4 v[66:67], v[36:39], off
	global_store_dwordx4 v[66:67], v[32:35], off offset:16
